# FoX loop top: cpre LDS read hoisted above the eight LDS stores and waited with a counted lgkmcnt(8) at its consumer
# speedup vs baseline: 1.0045x; 1.0045x over previous
;   DI float aux(int key) const { return (cuml[key] + cpre[key >> 7]) * LOG2E; }
;           DI float aux(int key) const { int n = key < 511 ? key : 510; return __int_as_float(pos[16 * n + 31]); }
;   DI int next(int t) const { for (int j = t + 1; j < 128; ++j) if (inu(j) && !farj(j)) return j; return -1; }
;   DI float aux(int key) const { return __int_as_float(pos[key]); }
;   DI int next(int t) const { for (int j = t + 1; j < 128; ++j) if (inu(j) && farj(j)) return j; return -1; }
;   DI float aux(int key) const { return __int_as_float(pos[key]); }
; template <int DK, bool PV, bool PF, class Ctx>
; DI void attn_run(const bf16x8 (&qf)[DK / 16], f32x16 (&o)[4], float& m, float& l, const bf16* K1, int ldk1,
;                  const bf16* K2, int ldk2, const bf16* Vt, int ldv, int first, Ctx& ctx, char* smem) {
;     ...
;     raux = (tid < 64) ? ctx.aux(key0 + tid) : 0.f;
;   };
;   auto sstore = [&]() {
;     stk(0, rk0); stk(1, rk1); stk(2, rk2); stk(3, rk3);
;     if (NKC > 4) { stk(4, rk4); stk(5, rk5); }
; #pragma unroll
;     for (int i = 0; i < 4; ++i) {
;       int c = tid + 256 * i;
;       int d = c >> 3, cc = c & 7;
;       uint2* dst = (uint2*)(Vs + d * 68 + cc * 8);
;       dst[0] = make_uint2(rv[i].x, rv[i].y);
;       dst[1] = make_uint2(rv[i].z, rv[i].w);
;     }
;     if (tid < 64) ((float*)(smem + AT_AUX))[tid] = raux;
;   };
;   if (PF) gload(tcur * 64);
;   while (tcur >= 0) {
;     __syncthreads();
;     if (!PF) gload(tcur * 64);
;     sstore();
;     __syncthreads();
;     int tnext = ctx.next(tcur);
;     if (PF && tnext >= 0) gload(tnext * 64);
.LBB0_333:
	s_barrier
	s_lshl_b32 s52, s26, 1
	s_andn2_b32 s52, s52, 3
	v_mov_b32_e32 v0, s52
	s_and_saveexec_b64 s[24:25], s[8:9]
	ds_read_b32 v0, v0 offset:43264
	s_or_b64 exec, exec, s[24:25]
	s_waitcnt vmcnt(6)
	ds_write_b128 v176, v[130:133]
	ds_write_b128 v177, v[134:137]
	s_waitcnt vmcnt(5)
	ds_write_b128 v178, v[138:141]
	s_waitcnt vmcnt(4)
	ds_write_b128 v179, v[142:145]
	s_waitcnt vmcnt(3)
	ds_write2_b64 v181, v[146:147], v[148:149] offset1:1
	s_waitcnt vmcnt(2)
	ds_write2_b64 v182, v[150:151], v[152:153] offset1:1
	s_waitcnt vmcnt(1)
	ds_write2_b64 v183, v[154:155], v[156:157] offset1:1
	s_waitcnt vmcnt(0)
	ds_write2_b64 v184, v[158:159], v[160:161] offset1:1
	s_and_saveexec_b64 s[24:25], s[8:9]
	s_waitcnt lgkmcnt(8)
	v_add_f32_e32 v0, v180, v0
	v_mul_f32_e32 v0, 0x3fb8aa3b, v0
	ds_write_b32 v169, v0 offset:43008
	s_or_b64 exec, exec, s[24:25]
	s_add_i32 s52, s26, 1
	s_cmp_le_u32 s26, s1
	s_cselect_b32 s26, s52, -1
	s_cmp_lt_i32 s26, 0
	s_cselect_b64 s[24:25], -1, 0
	s_and_b64 vcc, exec, s[24:25]
	s_waitcnt lgkmcnt(0)
	s_barrier
	s_cbranch_vccnz .LBB0_339
	s_lshl_b32 s64, s26, 6
	v_mov_b32_e32 v180, 0
	s_mul_i32 s26, s64, s70
	s_add_u32 s34, s12, s26
	s_addc_u32 s35, s13, 0
	global_load_dwordx4 v[130:133], v248, s[34:35]
	s_add_u32 s34, s34, 0x39000
	s_addc_u32 s35, s35, 0
	global_load_dwordx4 v[134:137], v248, s[34:35]
	s_add_u32 s34, s34, 0x39000
	s_addc_u32 s35, s35, 0
	global_load_dwordx4 v[138:141], v248, s[34:35]
	s_add_u32 s34, s34, 0x39000
	s_addc_u32 s35, s35, 0
	global_load_dwordx4 v[142:145], v248, s[34:35]
	s_lshl_b32 s26, s64, 1
	s_add_u32 s34, s22, s26
	s_addc_u32 s35, s23, 0
	global_load_dwordx4 v[146:149], v249, s[34:35]
	s_add_u32 s34, s34, 0x80000
	s_addc_u32 s35, s35, 0
	global_load_dwordx4 v[150:153], v249, s[34:35]
	s_add_u32 s34, s34, 0x80000
	s_addc_u32 s35, s35, 0
	global_load_dwordx4 v[154:157], v249, s[34:35]
	s_add_u32 s34, s34, 0x80000
	s_addc_u32 s35, s35, 0
	global_load_dwordx4 v[158:161], v249, s[34:35]
	s_lshl_b32 s26, s64, 2
	s_add_u32 s34, s20, s26
	s_addc_u32 s35, s21, 0
	s_and_saveexec_b64 s[26:27], s[8:9]
	global_load_dword v180, v169, s[34:35]
